# attention: Q-fragment loads and first K tile loads overlap (dropped the wait between them)
# speedup vs baseline: 1.0060x; 1.0053x over previous
.LBB0_499:
	s_or_b32 s86, s15, s33
	s_lshl_b64 s[6:7], s[86:87], 1
	v_lshl_add_u64 v[16:17], v[180:181], 0, s[6:7]
	global_load_dwordx4 v[112:115], v[16:17], off offset:96
	global_load_dwordx4 v[116:119], v[16:17], off offset:64
	global_load_dwordx4 v[120:123], v[16:17], off offset:32
	global_load_dwordx4 v[124:127], v[16:17], off
	s_add_u32 s84, s8, s6
	s_addc_u32 s85, s9, s7
	s_mov_b64 s[6:7], s[84:85]
	s_nop 0
	v_lshl_add_u64 v[16:17], s[6:7], 0, v[182:183]
	s_add_u32 s6, s84, 0x20000
	s_addc_u32 s7, s85, 0
	flat_load_dwordx4 v[16:19], v[16:17]
	s_nop 0
	v_lshl_add_u64 v[20:21], s[6:7], 0, v[182:183]
	flat_load_dwordx4 v[20:23], v[20:21]
	s_mov_b64 s[6:7], s[90:91]
	s_waitcnt vmcnt(0) lgkmcnt(0)
	ds_write_b128 v213, v[16:19]
	ds_write_b128 v213, v[20:23] offset:9216
	s_waitcnt lgkmcnt(0)
	s_barrier
	ds_read_b128 v[16:19], v208 offset:4608
	ds_read_b128 v[20:23], v208
	ds_read_b128 v[48:51], v208 offset:32
	ds_read_b128 v[52:55], v208 offset:4640
	ds_read_b128 v[56:59], v208 offset:64
	ds_read_b128 v[60:63], v208 offset:4672
	ds_read_b128 v[64:67], v208 offset:96
	ds_read_b128 v[68:71], v208 offset:4704
	s_waitcnt lgkmcnt(6)
	v_mfma_f32_32x32x16_bf16 v[32:47], v[20:23], v[124:127], 0
	s_waitcnt lgkmcnt(0)
	s_barrier
	v_mfma_f32_32x32x16_bf16 v[16:31], v[16:19], v[124:127], 0
	s_waitcnt lgkmcnt(5)
	v_mfma_f32_32x32x16_bf16 v[32:47], v[48:51], v[120:123], v[32:47]
	v_lshl_add_u64 v[48:49], s[6:7], 0, v[184:185]
	s_mov_b64 s[6:7], s[0:1]
	s_waitcnt lgkmcnt(4)
	v_mfma_f32_32x32x16_bf16 v[16:31], v[52:55], v[120:123], v[16:31]
	s_waitcnt lgkmcnt(3)
	v_mfma_f32_32x32x16_bf16 v[32:47], v[56:59], v[116:119], v[32:47]
	s_waitcnt lgkmcnt(2)
	v_mfma_f32_32x32x16_bf16 v[16:31], v[60:63], v[116:119], v[16:31]
	s_waitcnt lgkmcnt(1)
	v_mfma_f32_32x32x16_bf16 v[32:47], v[64:67], v[112:115], v[32:47]
	flat_load_dwordx4 v[64:67], v[48:49]
	s_nop 0
	v_lshl_add_u64 v[48:49], s[6:7], 0, v[184:185]
	s_add_u32 s6, s84, 0x40000
	s_addc_u32 s7, s85, 0
	s_waitcnt lgkmcnt(0)
	v_mfma_f32_32x32x16_bf16 v[16:31], v[68:71], v[112:115], v[16:31]
	flat_load_dwordx4 v[68:71], v[48:49]
	s_nop 0
	v_lshl_add_u64 v[48:49], s[6:7], 0, v[182:183]
	flat_load_dwordx4 v[144:147], v[48:49]
	s_and_saveexec_b64 s[6:7], s[4:5]
	s_cbranch_execz .LBB0_501
	v_sub_f32_e32 v47, v47, v15
	v_sub_f32_e32 v46, v46, v14
	v_sub_f32_e32 v45, v45, v13
	v_sub_f32_e32 v44, v44, v12
	v_sub_f32_e32 v43, v43, v11
	v_sub_f32_e32 v42, v42, v10
	v_sub_f32_e32 v41, v41, v9
	v_sub_f32_e32 v40, v40, v8
	v_sub_f32_e32 v39, v39, v7
	v_sub_f32_e32 v38, v38, v6
	v_sub_f32_e32 v37, v37, v5
	v_sub_f32_e32 v36, v36, v4
	v_sub_f32_e32 v35, v35, v3
	v_sub_f32_e32 v34, v34, v2
	v_sub_f32_e32 v33, v33, v1
	v_sub_f32_e32 v32, v32, v0
	v_sub_f32_e32 v31, v31, v15
	v_sub_f32_e32 v30, v30, v14
	v_sub_f32_e32 v29, v29, v13
	v_sub_f32_e32 v28, v28, v12
	v_sub_f32_e32 v27, v27, v11
	v_sub_f32_e32 v26, v26, v10
	v_sub_f32_e32 v25, v25, v9
	v_sub_f32_e32 v24, v24, v8
	v_sub_f32_e32 v23, v23, v7
	v_sub_f32_e32 v22, v22, v6
	v_sub_f32_e32 v21, v21, v5
	v_sub_f32_e32 v20, v20, v4
	v_sub_f32_e32 v19, v19, v3
	v_sub_f32_e32 v18, v18, v2
	v_sub_f32_e32 v17, v17, v1
	v_sub_f32_e32 v16, v16, v0

.LBB0_533:
	s_or_b32 s86, s15, s33
	s_lshl_b64 s[6:7], s[86:87], 1
	v_lshl_add_u64 v[16:17], v[180:181], 0, s[6:7]
	global_load_dwordx4 v[112:115], v[16:17], off offset:96
	global_load_dwordx4 v[116:119], v[16:17], off offset:64
	global_load_dwordx4 v[120:123], v[16:17], off offset:32
	global_load_dwordx4 v[124:127], v[16:17], off
	s_add_u32 s96, s8, s6
	s_addc_u32 s97, s9, s7
	s_mov_b64 s[6:7], s[96:97]
	s_nop 0
	v_lshl_add_u64 v[16:17], s[6:7], 0, v[182:183]
	s_add_u32 s6, s96, 0x20000
	s_addc_u32 s7, s97, 0
	flat_load_dwordx4 v[16:19], v[16:17]
	s_nop 0
	v_lshl_add_u64 v[20:21], s[6:7], 0, v[182:183]
	flat_load_dwordx4 v[20:23], v[20:21]
	s_mov_b64 s[6:7], s[90:91]
	s_waitcnt vmcnt(0) lgkmcnt(0)
	ds_write_b128 v213, v[16:19]
	ds_write_b128 v213, v[20:23] offset:9216
	s_waitcnt lgkmcnt(0)
	s_barrier
	ds_read_b128 v[16:19], v208 offset:4608
	ds_read_b128 v[20:23], v208
	ds_read_b128 v[48:51], v208 offset:32
	ds_read_b128 v[52:55], v208 offset:4640
	ds_read_b128 v[56:59], v208 offset:64
	ds_read_b128 v[60:63], v208 offset:4672
	ds_read_b128 v[64:67], v208 offset:96
	ds_read_b128 v[68:71], v208 offset:4704
	s_waitcnt lgkmcnt(6)
	v_mfma_f32_32x32x16_bf16 v[32:47], v[20:23], v[124:127], 0
	s_waitcnt lgkmcnt(0)
	s_barrier
	v_mfma_f32_32x32x16_bf16 v[16:31], v[16:19], v[124:127], 0
	s_waitcnt lgkmcnt(5)
	v_mfma_f32_32x32x16_bf16 v[32:47], v[48:51], v[120:123], v[32:47]
	v_lshl_add_u64 v[48:49], s[6:7], 0, v[184:185]
	s_mov_b64 s[6:7], s[0:1]
	s_waitcnt lgkmcnt(4)
	v_mfma_f32_32x32x16_bf16 v[16:31], v[52:55], v[120:123], v[16:31]
	s_waitcnt lgkmcnt(3)
	v_mfma_f32_32x32x16_bf16 v[32:47], v[56:59], v[116:119], v[32:47]
	s_waitcnt lgkmcnt(2)
	v_mfma_f32_32x32x16_bf16 v[16:31], v[60:63], v[116:119], v[16:31]
	s_waitcnt lgkmcnt(1)
	v_mfma_f32_32x32x16_bf16 v[32:47], v[64:67], v[112:115], v[32:47]
	flat_load_dwordx4 v[64:67], v[48:49]
	s_nop 0
	v_lshl_add_u64 v[48:49], s[6:7], 0, v[184:185]
	s_add_u32 s6, s96, 0x40000
	s_addc_u32 s7, s97, 0
	s_waitcnt lgkmcnt(0)
	v_mfma_f32_32x32x16_bf16 v[16:31], v[68:71], v[112:115], v[16:31]
	flat_load_dwordx4 v[68:71], v[48:49]
	s_nop 0
	v_lshl_add_u64 v[48:49], s[6:7], 0, v[182:183]
	flat_load_dwordx4 v[144:147], v[48:49]
	s_and_saveexec_b64 s[6:7], s[4:5]
	s_cbranch_execz .LBB0_535
	v_sub_f32_e32 v47, v47, v15
	v_sub_f32_e32 v46, v46, v14
	v_sub_f32_e32 v45, v45, v13
	v_sub_f32_e32 v44, v44, v12
	v_sub_f32_e32 v43, v43, v11
	v_sub_f32_e32 v42, v42, v10
	v_sub_f32_e32 v41, v41, v9
	v_sub_f32_e32 v40, v40, v8
	v_sub_f32_e32 v39, v39, v7
	v_sub_f32_e32 v38, v38, v6
	v_sub_f32_e32 v37, v37, v5
	v_sub_f32_e32 v36, v36, v4
	v_sub_f32_e32 v35, v35, v3
	v_sub_f32_e32 v34, v34, v2
	v_sub_f32_e32 v33, v33, v1
	v_sub_f32_e32 v32, v32, v0
	v_sub_f32_e32 v31, v31, v15
	v_sub_f32_e32 v30, v30, v14
	v_sub_f32_e32 v29, v29, v13
	v_sub_f32_e32 v28, v28, v12
	v_sub_f32_e32 v27, v27, v11
	v_sub_f32_e32 v26, v26, v10
	v_sub_f32_e32 v25, v25, v9
	v_sub_f32_e32 v24, v24, v8
	v_sub_f32_e32 v23, v23, v7
	v_sub_f32_e32 v22, v22, v6
	v_sub_f32_e32 v21, v21, v5
	v_sub_f32_e32 v20, v20, v4
	v_sub_f32_e32 v19, v19, v3
	v_sub_f32_e32 v18, v18, v2
	v_sub_f32_e32 v17, v17, v1
	v_sub_f32_e32 v16, v16, v0
